# v61 + 12288 gate2/up2 tiles leave the P5 queue: even WGs convert half before their P4 units, odd WGs the other half after theirs (HBM-bound conversion overlapped with compute-bound chunk-local phase)
# baseline (speedup 1.0000x reference)
; #define REFRESH_IDS() do { lane = fresh_lane(); tid = wave * 64 + lane; } while (0)
; __global__ void __launch_bounds__(NWAVES * 64, 2) fwd(Args args) {
;     ...
;     if (IN(4)) {
;         REFRESH_IDS();
.LBB0_489:
	s_cmp_lt_i32 s96, 5
	s_cselect_b64 s[2:3], -1, 0
	s_cmp_gt_i32 s97, 4
	s_cselect_b64 s[4:5], -1, 0
	s_and_b64 s[2:3], s[2:3], s[4:5]
	s_andn2_b64 vcc, exec, s[2:3]
	s_cbranch_vccnz .LBB0_621
	s_bitcmp1_b32 s8, 0
	s_cbranch_scc1 .Lhcs_done
	v_writelane_b32 v238, s0, 0
	v_writelane_b32 v238, s1, 1
	v_writelane_b32 v238, s2, 2
	v_writelane_b32 v238, s3, 3
	v_writelane_b32 v238, s4, 4
	v_writelane_b32 v238, s5, 5
	v_writelane_b32 v238, s6, 6
	v_writelane_b32 v238, s7, 7
	v_writelane_b32 v238, s8, 8
	v_writelane_b32 v238, s9, 9
	v_writelane_b32 v238, s10, 10
	v_writelane_b32 v238, s11, 11
	v_writelane_b32 v238, s12, 12
	v_writelane_b32 v238, s13, 13
	v_writelane_b32 v238, s14, 14
	v_writelane_b32 v238, s15, 15
	v_writelane_b32 v238, s16, 16
	v_writelane_b32 v238, s17, 17
	v_writelane_b32 v238, s18, 18
	v_writelane_b32 v238, s19, 19
	v_writelane_b32 v238, s20, 20
	v_writelane_b32 v238, s21, 21
	v_writelane_b32 v238, s22, 22
	v_writelane_b32 v238, s23, 23
	v_writelane_b32 v238, s24, 24
	v_writelane_b32 v238, s25, 25
	v_writelane_b32 v238, s26, 26
	v_writelane_b32 v238, s27, 27
	v_writelane_b32 v238, s28, 28
	v_writelane_b32 v238, s29, 29
	v_writelane_b32 v238, s30, 30
	v_writelane_b32 v238, s31, 31
	v_writelane_b32 v238, s32, 32
	v_writelane_b32 v238, s33, 33
	v_writelane_b32 v238, s34, 34
	v_writelane_b32 v238, s35, 35
	v_writelane_b32 v238, s36, 36
	v_writelane_b32 v238, s37, 37
	v_writelane_b32 v238, s38, 38
	v_writelane_b32 v238, s39, 39
	v_writelane_b32 v238, s40, 40
	v_writelane_b32 v238, s41, 41
	v_writelane_b32 v238, s42, 42
	v_writelane_b32 v238, s43, 43
	v_writelane_b32 v238, s44, 44
	v_writelane_b32 v238, s45, 45
	v_writelane_b32 v238, s46, 46
	v_writelane_b32 v238, s47, 47
	v_writelane_b32 v238, s48, 48
	v_writelane_b32 v238, s49, 49
	v_writelane_b32 v238, s50, 50
	v_writelane_b32 v238, s51, 51
	v_writelane_b32 v238, s52, 52
	v_writelane_b32 v238, s53, 53
	v_writelane_b32 v238, s54, 54
	v_writelane_b32 v238, s55, 55
	v_writelane_b32 v238, s56, 56
	v_writelane_b32 v238, s57, 57
	v_writelane_b32 v238, s58, 58
	v_writelane_b32 v238, s59, 59
	v_writelane_b32 v238, s60, 60
	v_writelane_b32 v238, s61, 61
	v_writelane_b32 v238, s62, 62
	v_writelane_b32 v238, s63, 63
	v_writelane_b32 v239, s64, 0
	v_writelane_b32 v239, s65, 1
	v_writelane_b32 v239, s66, 2
	v_writelane_b32 v239, s67, 3
	v_writelane_b32 v239, s68, 4
	v_writelane_b32 v239, s69, 5
	v_writelane_b32 v239, s70, 6
	v_writelane_b32 v239, s71, 7
	v_writelane_b32 v239, s72, 8
	v_writelane_b32 v239, s73, 9
	v_writelane_b32 v239, s74, 10
	v_writelane_b32 v239, s75, 11
	v_writelane_b32 v239, s76, 12
	v_writelane_b32 v239, s77, 13
	v_writelane_b32 v239, s78, 14
	v_writelane_b32 v239, s79, 15
	v_writelane_b32 v239, s80, 16
	v_writelane_b32 v239, s81, 17
	v_writelane_b32 v239, s82, 18
	v_writelane_b32 v239, s83, 19
	v_writelane_b32 v239, s84, 20
	v_writelane_b32 v239, s85, 21
	v_writelane_b32 v239, s86, 22
	v_writelane_b32 v239, s87, 23
	v_writelane_b32 v239, s88, 24
	v_writelane_b32 v239, s89, 25
	v_writelane_b32 v239, s90, 26
	v_writelane_b32 v239, s91, 27
	v_writelane_b32 v239, s92, 28
	v_writelane_b32 v239, s93, 29
	v_writelane_b32 v239, s94, 30
	v_writelane_b32 v239, s95, 31
	v_writelane_b32 v239, s96, 32
	v_writelane_b32 v239, s97, 33
	v_writelane_b32 v239, s98, 34
	v_writelane_b32 v239, s99, 35
	v_writelane_b32 v239, s100, 36
	v_writelane_b32 v239, s101, 37
	v_writelane_b32 v239, vcc_lo, 38
	v_writelane_b32 v239, vcc_hi, 39
	v_writelane_b32 v239, m0, 40
	v_writelane_b32 v239, exec_lo, 41
	v_writelane_b32 v239, exec_hi, 42
	s_mov_b64 exec, -1
	s_lshr_b32 s75, s8, 1
	s_movk_i32 s33, 0x80
	s_lshl_b32 s9, s28, 6
	s_lshl_b32 s4, s75, 3
	s_add_i32 s16, s4, s28
	s_lshl_b32 s18, s33, 3
	s_add_u32 s6, s14, 0x40000
	s_addc_u32 s7, s15, 0
	s_add_u32 s36, s14, 0x400000
	s_addc_u32 s37, s15, 0
	s_add_u32 s34, s14, 0xb400000
	s_addc_u32 s35, s15, 0
	s_load_dwordx2 s[96:97], s[0:1], 0x98
	s_add_u32 s10, s14, 0x10c00000
	s_addc_u32 s11, s15, 0
	s_add_u32 s26, s14, 0x2a800000
	s_addc_u32 s27, s15, 0
	s_waitcnt lgkmcnt(0)
	s_cmp_lt_i32 s96, 1
	s_cselect_b64 s[4:5], -1, 0
	s_cmp_gt_i32 s97, 0
	s_cselect_b64 s[20:21], -1, 0
	s_and_b64 s[4:5], s[4:5], s[20:21]
	s_and_b64 vcc, exec, s[4:5]
	s_mul_i32 s74, s28, 0x4100
	s_cbranch_vccz .Lhcs_end
	s_abs_i32 s4, s18
	v_cvt_f32_u32_e32 v0, s4
	s_sub_i32 s5, 0, s4
	s_add_i32 s19, s74, 0
	v_mbcnt_lo_u32_b32 v140, -1, 0
	v_mbcnt_hi_u32_b32 v140, -1, v140
	v_rcp_iflag_f32_e32 v0, v0
	s_nop 0
	v_mul_f32_e32 v0, 0x4f7ffffe, v0
	v_cvt_u32_f32_e32 v0, v0
	s_nop 0
	v_readfirstlane_b32 s17, v0
	s_mul_i32 s5, s5, s17
	s_mul_hi_u32 s5, s17, s5
	s_add_i32 s17, s17, s5
	s_mul_hi_u32 s5, s17, 0x9c4e
	s_mul_i32 s5, s5, s4
	s_sub_i32 s5, 0x9c4e, s5
	s_sub_i32 s17, s5, s4
	s_cmp_ge_u32 s5, s4
	s_cselect_b32 s5, s17, s5
	s_sub_i32 s17, s5, s4
	s_cmp_ge_u32 s5, s4
	s_cselect_b32 s23, s17, s5
	s_sub_i32 s22, 0x9c4e, s23
	s_add_i32 s16, s16, 0x0
	s_mov_b32 s22, 0x1800
	s_add_u32 s0, s0, 88
	s_addc_u32 s1, s1, 0
	s_add_u32 s36, s14, 0x1a000000
	s_addc_u32 s37, s15, 0
	s_cmp_ge_i32 s16, s22
	s_cbranch_scc1 .Lhcs_end
	s_cmpk_gt_i32 s16, 0x55ff
	s_cbranch_scc0 .Lhcs_14
	s_cmpk_gt_u32 s16, 0x80ff
	s_cbranch_scc0 .Lhcs_15
	s_add_u32 s42, s0, 48
	s_addc_u32 s43, s1, 0
	s_add_i32 s17, s16, 0x7f00
	s_and_b32 s20, s17, 0xffff
	s_mul_i32 s20, s20, 0x91a3
	s_load_dwordx2 s[4:5], s[0:1], 0x28
	s_lshr_b32 s20, s20, 23
	s_lshl_b32 s30, s20, 6
	s_mulk_i32 s20, 0xe1
	s_sub_i32 s17, s17, s20
	s_lshl_b32 s17, s17, 6
	s_and_b32 s17, s17, 0xffc0
	s_cbranch_execz .Lhcs_16
	s_movk_i32 s25, 0x1040
	s_movk_i32 s24, 0x3820
	s_mov_b64 s[40:41], s[10:11]
	s_branch .Lhcs_17

; #define REFRESH_IDS() do { lane = fresh_lane(); tid = wave * 64 + lane; } while (0)
; __global__ void __launch_bounds__(NWAVES * 64, 2) fwd(Args args) {
;     ...
;     if (IN(4)) {
;         REFRESH_IDS();
;         { u32x4 xr[24]; float gpre, bpre; int sh0 = -1, sh1 = -1, it = 0;
;           CL_PREFETCH(vcu);
.Lhcs_end:
	s_waitcnt vmcnt(0) lgkmcnt(0)
	v_readlane_b32 s2, v239, 40
	s_mov_b32 m0, s2
	v_readlane_b32 s2, v239, 41
	v_readlane_b32 s3, v239, 42
	s_mov_b64 exec, s[2:3]
	v_readlane_b32 s0, v238, 0
	v_readlane_b32 s1, v238, 1
	v_readlane_b32 s2, v238, 2
	v_readlane_b32 s3, v238, 3
	v_readlane_b32 s4, v238, 4
	v_readlane_b32 s5, v238, 5
	v_readlane_b32 s6, v238, 6
	v_readlane_b32 s7, v238, 7
	v_readlane_b32 s8, v238, 8
	v_readlane_b32 s9, v238, 9
	v_readlane_b32 s10, v238, 10
	v_readlane_b32 s11, v238, 11
	v_readlane_b32 s12, v238, 12
	v_readlane_b32 s13, v238, 13
	v_readlane_b32 s14, v238, 14
	v_readlane_b32 s15, v238, 15
	v_readlane_b32 s16, v238, 16
	v_readlane_b32 s17, v238, 17
	v_readlane_b32 s18, v238, 18
	v_readlane_b32 s19, v238, 19
	v_readlane_b32 s20, v238, 20
	v_readlane_b32 s21, v238, 21
	v_readlane_b32 s22, v238, 22
	v_readlane_b32 s23, v238, 23
	v_readlane_b32 s24, v238, 24
	v_readlane_b32 s25, v238, 25
	v_readlane_b32 s26, v238, 26
	v_readlane_b32 s27, v238, 27
	v_readlane_b32 s28, v238, 28
	v_readlane_b32 s29, v238, 29
	v_readlane_b32 s30, v238, 30
	v_readlane_b32 s31, v238, 31
	v_readlane_b32 s32, v238, 32
	v_readlane_b32 s33, v238, 33
	v_readlane_b32 s34, v238, 34
	v_readlane_b32 s35, v238, 35
	v_readlane_b32 s36, v238, 36
	v_readlane_b32 s37, v238, 37
	v_readlane_b32 s38, v238, 38
	v_readlane_b32 s39, v238, 39
	v_readlane_b32 s40, v238, 40
	v_readlane_b32 s41, v238, 41
	v_readlane_b32 s42, v238, 42
	v_readlane_b32 s43, v238, 43
	v_readlane_b32 s44, v238, 44
	v_readlane_b32 s45, v238, 45
	v_readlane_b32 s46, v238, 46
	v_readlane_b32 s47, v238, 47
	v_readlane_b32 s48, v238, 48
	v_readlane_b32 s49, v238, 49
	v_readlane_b32 s50, v238, 50
	v_readlane_b32 s51, v238, 51
	v_readlane_b32 s52, v238, 52
	v_readlane_b32 s53, v238, 53
	v_readlane_b32 s54, v238, 54
	v_readlane_b32 s55, v238, 55
	v_readlane_b32 s56, v238, 56
	v_readlane_b32 s57, v238, 57
	v_readlane_b32 s58, v238, 58
	v_readlane_b32 s59, v238, 59
	v_readlane_b32 s60, v238, 60
	v_readlane_b32 s61, v238, 61
	v_readlane_b32 s62, v238, 62
	v_readlane_b32 s63, v238, 63
	v_readlane_b32 s64, v239, 0
	v_readlane_b32 s65, v239, 1
	v_readlane_b32 s66, v239, 2
	v_readlane_b32 s67, v239, 3
	v_readlane_b32 s68, v239, 4
	v_readlane_b32 s69, v239, 5
	v_readlane_b32 s70, v239, 6
	v_readlane_b32 s71, v239, 7
	v_readlane_b32 s72, v239, 8
	v_readlane_b32 s73, v239, 9
	v_readlane_b32 s74, v239, 10
	v_readlane_b32 s75, v239, 11
	v_readlane_b32 s76, v239, 12
	v_readlane_b32 s77, v239, 13
	v_readlane_b32 s78, v239, 14
	v_readlane_b32 s79, v239, 15
	v_readlane_b32 s80, v239, 16
	v_readlane_b32 s81, v239, 17
	v_readlane_b32 s82, v239, 18
	v_readlane_b32 s83, v239, 19
	v_readlane_b32 s84, v239, 20
	v_readlane_b32 s85, v239, 21
	v_readlane_b32 s86, v239, 22
	v_readlane_b32 s87, v239, 23
	v_readlane_b32 s88, v239, 24
	v_readlane_b32 s89, v239, 25
	v_readlane_b32 s90, v239, 26
	v_readlane_b32 s91, v239, 27
	v_readlane_b32 s92, v239, 28
	v_readlane_b32 s93, v239, 29
	v_readlane_b32 s94, v239, 30
	v_readlane_b32 s95, v239, 31
	v_readlane_b32 s96, v239, 32
	v_readlane_b32 s97, v239, 33
	v_readlane_b32 s98, v239, 34
	v_readlane_b32 s99, v239, 35
	v_readlane_b32 s100, v239, 36
	v_readlane_b32 s101, v239, 37
	v_readlane_b32 vcc_lo, v239, 38
	v_readlane_b32 vcc_hi, v239, 39
	s_barrier
; __global__ void __launch_bounds__(NWAVES * 64, 2) fwd(Args args) {
;     ...
;         { u32x4 xr[24]; float gpre, bpre; int sh0 = -1, sh1 = -1, it = 0;
;           CL_PREFETCH(vcu);
;           for (int unit = vcu; unit < 2048; unit += G, ++it) { const int nxt = unit + G < 2048 ? unit + G : unit;
;               dn_chunk_local(unit, nxt, it & 1, sh0, sh1, xr, gpre, bpre, PROJ, args.in[7], GLOG, BETA, DNB, L, tid, lane, wave); } }
.Lhcs_done:
	s_cmpk_gt_i32 s75, 0x7ff
	v_mbcnt_lo_u32_b32 v134, -1, 0
	v_mbcnt_hi_u32_b32 v134, -1, v134
	s_cbranch_scc1 .LBB0_565
	s_add_u32 s36, s14, 0x200000
	s_addc_u32 s37, s15, 0
	s_add_u32 s38, s14, 0x280000
	s_addc_u32 s39, s15, 0
	s_lshl_b32 s2, s75, 2
	s_lshl_b32 s3, s75, 6
	v_add_u32_e32 v135, s9, v134
	s_and_b32 s2, s2, 0xfffff800
	s_and_b32 s6, s3, 0x7c0
	v_ashrrev_i32_e32 v8, 3, v135
	s_or_b32 s2, s2, s6
	v_add_u32_e32 v12, s2, v8
	s_movk_i32 s17, 0x7080
	s_waitcnt lgkmcnt(0)
	v_mov_b64_e32 v[0:1], s[34:35]
	s_bfe_u32 s3, s75, 0x40005
	v_mad_i64_i32 v[2:3], s[4:5], v12, s17, v[0:1]
	s_lshl_b32 s40, s3, 8
	s_mov_b32 s41, 0
	v_lshlrev_b32_e32 v4, 5, v134
	v_and_b32_e32 v128, 0xe0, v4
	v_mov_b32_e32 v129, 0
	v_lshl_add_u64 v[2:3], v[2:3], 0, s[40:41]
	v_lshl_add_u64 v[2:3], v[2:3], 0, v[128:129]
	s_movk_i32 s19, 0x5000
	v_add_co_u32_e32 v6, vcc, s19, v2
	s_mov_b64 s[42:43], 0x5000
	s_nop 0
	v_addc_co_u32_e32 v7, vcc, 0, v3, vcc
	v_add_u32_e32 v13, s6, v8
	v_lshl_add_u64 v[4:5], v[2:3], 0, s[42:43]
	v_cmp_lt_i32_e32 vcc, 0, v13
	global_load_dwordx4 v[24:27], v[6:7], off
	global_load_dwordx4 v[20:23], v[4:5], off offset:16
	v_subbrev_co_u32_e32 v4, vcc, 0, v12, vcc
	v_mad_i64_i32 v[4:5], s[4:5], v4, s17, v[0:1]
	v_lshl_add_u64 v[4:5], v[4:5], 0, s[40:41]
	v_lshl_add_u64 v[4:5], v[4:5], 0, v[128:129]
	v_add_co_u32_e32 v8, vcc, s19, v4
	v_lshl_add_u64 v[6:7], v[4:5], 0, s[42:43]
	s_nop 0
	v_addc_co_u32_e32 v9, vcc, 0, v5, vcc
	v_cmp_gt_i32_e32 vcc, 2, v13
	global_load_dwordx4 v[32:35], v[8:9], off
	global_load_dwordx4 v[28:31], v[6:7], off offset:16
	v_cndmask_b32_e64 v6, -2, 0, vcc
	v_add_u32_e32 v6, v12, v6
	v_mad_i64_i32 v[6:7], s[4:5], v6, s17, v[0:1]
	v_lshl_add_u64 v[6:7], v[6:7], 0, s[40:41]
	v_lshl_add_u64 v[6:7], v[6:7], 0, v[128:129]
	v_add_co_u32_e32 v10, vcc, s19, v6
	v_lshl_add_u64 v[8:9], v[6:7], 0, s[42:43]
	s_nop 0
	v_addc_co_u32_e32 v11, vcc, 0, v7, vcc
	v_cmp_gt_i32_e32 vcc, 3, v13
	global_load_dwordx4 v[40:43], v[10:11], off
	global_load_dwordx4 v[36:39], v[8:9], off offset:16
	v_cndmask_b32_e64 v8, -3, 0, vcc
	v_add_u32_e32 v8, v12, v8
	v_mad_i64_i32 v[0:1], s[4:5], v8, s17, v[0:1]
	v_lshl_add_u64 v[0:1], v[0:1], 0, s[40:41]
	v_lshl_add_u64 v[0:1], v[0:1], 0, v[128:129]
	v_add_co_u32_e32 v10, vcc, s19, v0
	s_movk_i32 s22, 0x4000
	s_nop 0
	v_addc_co_u32_e32 v11, vcc, 0, v1, vcc
	v_lshl_add_u64 v[8:9], v[0:1], 0, s[42:43]
	global_load_dwordx4 v[48:51], v[10:11], off
	global_load_dwordx4 v[44:47], v[8:9], off offset:16
	v_add_co_u32_e32 v10, vcc, s22, v2
	s_mov_b64 s[44:45], 0x4000
	s_nop 0
	v_addc_co_u32_e32 v11, vcc, 0, v3, vcc
	v_lshl_add_u64 v[8:9], v[2:3], 0, s[44:45]
	global_load_dwordx4 v[56:59], v[10:11], off
	global_load_dwordx4 v[52:55], v[8:9], off offset:16
	v_add_co_u32_e32 v10, vcc, s22, v4
	v_lshl_add_u64 v[8:9], v[4:5], 0, s[44:45]
	s_nop 0
	v_addc_co_u32_e32 v11, vcc, 0, v5, vcc
	global_load_dwordx4 v[64:67], v[10:11], off
	global_load_dwordx4 v[60:63], v[8:9], off offset:16
	v_add_co_u32_e32 v10, vcc, s22, v6
	v_lshl_add_u64 v[8:9], v[6:7], 0, s[44:45]
	s_nop 0
	v_addc_co_u32_e32 v11, vcc, 0, v7, vcc
	global_load_dwordx4 v[72:75], v[10:11], off
	global_load_dwordx4 v[68:71], v[8:9], off offset:16
	v_add_co_u32_e32 v10, vcc, s22, v0
	v_lshl_add_u64 v[8:9], v[0:1], 0, s[44:45]
	s_nop 0
	v_addc_co_u32_e32 v11, vcc, 0, v1, vcc
	s_mov_b64 s[46:47], 0x3000
	s_movk_i32 s4, 0x3000
	global_load_dwordx4 v[80:83], v[10:11], off
	global_load_dwordx4 v[76:79], v[8:9], off offset:16
	v_lshl_add_u64 v[8:9], v[2:3], 0, s[46:47]
	v_add_co_u32_e32 v2, vcc, s4, v2
	s_mov_b32 s23, -1
	s_nop 0
	v_addc_co_u32_e32 v3, vcc, 0, v3, vcc
	global_load_dwordx4 v[88:91], v[2:3], off
	global_load_dwordx4 v[84:87], v[8:9], off offset:16
	v_lshl_add_u64 v[2:3], v[4:5], 0, s[46:47]
	v_add_co_u32_e32 v4, vcc, s4, v4
	s_mov_b64 s[50:51], 0
	s_nop 0
	v_addc_co_u32_e32 v5, vcc, 0, v5, vcc
	global_load_dwordx4 v[96:99], v[4:5], off
	global_load_dwordx4 v[92:95], v[2:3], off offset:16
	v_add_co_u32_e32 v4, vcc, s4, v6
	v_lshl_add_u64 v[2:3], v[6:7], 0, s[46:47]
	s_nop 0
	v_addc_co_u32_e32 v5, vcc, 0, v7, vcc
	global_load_dwordx4 v[104:107], v[4:5], off
	global_load_dwordx4 v[100:103], v[2:3], off offset:16
	v_lshl_add_u64 v[2:3], v[0:1], 0, s[46:47]
	v_add_co_u32_e32 v0, vcc, s4, v0
	s_movk_i32 s24, 0x1800
	s_nop 0
	v_addc_co_u32_e32 v1, vcc, 0, v1, vcc
	global_load_dwordx4 v[112:115], v[0:1], off
	global_load_dwordx4 v[108:111], v[2:3], off offset:16
	v_add_u32_e32 v0, s2, v134
	v_ashrrev_i32_e32 v1, 31, v0
	v_lshlrev_b64 v[0:1], 6, v[0:1]
	v_lshl_or_b32 v0, s3, 2, v0
	v_lshl_add_u64 v[2:3], s[36:37], 0, v[0:1]
	v_lshl_add_u64 v[0:1], s[38:39], 0, v[0:1]
	global_load_dword v133, v[2:3], off
	global_load_dword v142, v[0:1], off
	s_load_dwordx2 s[48:49], s[0:1], 0x38
	v_mbcnt_lo_u32_b32 v0, -1, 0
	v_mbcnt_hi_u32_b32 v136, -1, v0
	v_bfrev_b32_e32 v0, 0.5
	s_movk_i32 s25, 0x1ff
	s_add_i32 s29, 0, 0x20800
	s_movk_i32 s55, 0x3ff
	v_lshl_or_b32 v137, v136, 2, v0
	s_movk_i32 s64, 0x110
	s_movk_i32 s65, 0x108
	s_mov_b64 s[52:53], 0x4200
	s_mov_b32 s54, 0xbfb8aa3b
	s_mov_b32 s66, 0x800000
	s_movk_i32 s67, 0x88
	s_add_i32 s68, 0, 0x1c800
	s_add_i32 s69, 0, 0x11800
	s_movk_i32 s70, 0x50
	s_add_i32 s71, 0, 0x1f400
	s_movk_i32 s72, 0xf600
	s_movk_i32 s73, 0x180
	s_movk_i32 s77, 0x80
	s_movk_i32 s78, 0x90
	s_movk_i32 s79, 0x4c0
	s_add_i32 s80, 0, 0x1c400
	s_movk_i32 s81, 0xfe90
	s_movk_i32 s82, 0x2bf
	s_movk_i32 s83, 0x480
	s_mov_b64 s[56:57], 0xa600
	s_movk_i32 s84, 0x27f
	s_movk_i32 s85, 0x48
	s_add_i32 s86, 0, 0x1ea00
	s_add_i32 s87, 0, 0x1a400
	s_movk_i32 s88, 0x120
	s_mov_b64 s[58:59], 0xea00
	s_movk_i32 s89, 0x420
	s_movk_i32 s90, 0x21f
	v_mov_b32_e32 v138, 0x18000
	v_mov_b32_e32 v139, 0x15c00
	v_mov_b32_e32 v166, v129
	v_mov_b32_e32 v167, v129
	v_mov_b32_e32 v168, v129
	v_mov_b32_e32 v169, v129
	v_mov_b32_e32 v140, 0xfffffc00
	s_mov_b32 s91, 0
	s_mov_b32 s40, s75
	s_mov_b32 s92, -1
	s_branch .LBB0_493

; #define GRID_BAR() xcd_barrier(bar)
; #define GRID_BAR() do { } while (0)
; #define BOTH(k) (IN(k) && IN((k) + 1))
; __global__ void __launch_bounds__(NWAVES * 64, 2) fwd(Args args) {
;     ...
;           for (int unit = vcu; unit < 2048; unit += G, ++it) { const int nxt = unit + G < 2048 ? unit + G : unit;
;               dn_chunk_local(unit, nxt, it & 1, sh0, sh1, xr, gpre, bpre, PROJ, args.in[7], GLOG, BETA, DNB, L, tid, lane, wave); } }
;         if (BOTH(4)) GRID_BAR();
;     }
.LBB0_565:
	s_bitcmp1_b32 s8, 0
	s_cbranch_scc0 .Lhce_done
	s_waitcnt lgkmcnt(0)
	s_barrier
	v_writelane_b32 v238, s0, 0
	v_writelane_b32 v238, s1, 1
	v_writelane_b32 v238, s2, 2
	v_writelane_b32 v238, s3, 3
	v_writelane_b32 v238, s4, 4
	v_writelane_b32 v238, s5, 5
	v_writelane_b32 v238, s6, 6
	v_writelane_b32 v238, s7, 7
	v_writelane_b32 v238, s8, 8
	v_writelane_b32 v238, s9, 9
	v_writelane_b32 v238, s10, 10
	v_writelane_b32 v238, s11, 11
	v_writelane_b32 v238, s12, 12
	v_writelane_b32 v238, s13, 13
	v_writelane_b32 v238, s14, 14
	v_writelane_b32 v238, s15, 15
	v_writelane_b32 v238, s16, 16
	v_writelane_b32 v238, s17, 17
	v_writelane_b32 v238, s18, 18
	v_writelane_b32 v238, s19, 19
	v_writelane_b32 v238, s20, 20
	v_writelane_b32 v238, s21, 21
	v_writelane_b32 v238, s22, 22
	v_writelane_b32 v238, s23, 23
	v_writelane_b32 v238, s24, 24
	v_writelane_b32 v238, s25, 25
	v_writelane_b32 v238, s26, 26
	v_writelane_b32 v238, s27, 27
	v_writelane_b32 v238, s28, 28
	v_writelane_b32 v238, s29, 29
	v_writelane_b32 v238, s30, 30
	v_writelane_b32 v238, s31, 31
	v_writelane_b32 v238, s32, 32
	v_writelane_b32 v238, s33, 33
	v_writelane_b32 v238, s34, 34
	v_writelane_b32 v238, s35, 35
	v_writelane_b32 v238, s36, 36
	v_writelane_b32 v238, s37, 37
	v_writelane_b32 v238, s38, 38
	v_writelane_b32 v238, s39, 39
	v_writelane_b32 v238, s40, 40
	v_writelane_b32 v238, s41, 41
	v_writelane_b32 v238, s42, 42
	v_writelane_b32 v238, s43, 43
	v_writelane_b32 v238, s44, 44
	v_writelane_b32 v238, s45, 45
	v_writelane_b32 v238, s46, 46
	v_writelane_b32 v238, s47, 47
	v_writelane_b32 v238, s48, 48
	v_writelane_b32 v238, s49, 49
	v_writelane_b32 v238, s50, 50
	v_writelane_b32 v238, s51, 51
	v_writelane_b32 v238, s52, 52
	v_writelane_b32 v238, s53, 53
	v_writelane_b32 v238, s54, 54
	v_writelane_b32 v238, s55, 55
	v_writelane_b32 v238, s56, 56
	v_writelane_b32 v238, s57, 57
	v_writelane_b32 v238, s58, 58
	v_writelane_b32 v238, s59, 59
	v_writelane_b32 v238, s60, 60
	v_writelane_b32 v238, s61, 61
	v_writelane_b32 v238, s62, 62
	v_writelane_b32 v238, s63, 63
	v_writelane_b32 v239, s64, 0
	v_writelane_b32 v239, s65, 1
	v_writelane_b32 v239, s66, 2
	v_writelane_b32 v239, s67, 3
	v_writelane_b32 v239, s68, 4
	v_writelane_b32 v239, s69, 5
	v_writelane_b32 v239, s70, 6
	v_writelane_b32 v239, s71, 7
	v_writelane_b32 v239, s72, 8
	v_writelane_b32 v239, s73, 9
	v_writelane_b32 v239, s74, 10
	v_writelane_b32 v239, s75, 11
	v_writelane_b32 v239, s76, 12
	v_writelane_b32 v239, s77, 13
	v_writelane_b32 v239, s78, 14
	v_writelane_b32 v239, s79, 15
	v_writelane_b32 v239, s80, 16
	v_writelane_b32 v239, s81, 17
	v_writelane_b32 v239, s82, 18
	v_writelane_b32 v239, s83, 19
	v_writelane_b32 v239, s84, 20
	v_writelane_b32 v239, s85, 21
	v_writelane_b32 v239, s86, 22
	v_writelane_b32 v239, s87, 23
	v_writelane_b32 v239, s88, 24
	v_writelane_b32 v239, s89, 25
	v_writelane_b32 v239, s90, 26
	v_writelane_b32 v239, s91, 27
	v_writelane_b32 v239, s92, 28
	v_writelane_b32 v239, s93, 29
	v_writelane_b32 v239, s94, 30
	v_writelane_b32 v239, s95, 31
	v_writelane_b32 v239, s96, 32
	v_writelane_b32 v239, s97, 33
	v_writelane_b32 v239, s98, 34
	v_writelane_b32 v239, s99, 35
	v_writelane_b32 v239, s100, 36
	v_writelane_b32 v239, s101, 37
	v_writelane_b32 v239, vcc_lo, 38
	v_writelane_b32 v239, vcc_hi, 39
	v_writelane_b32 v239, m0, 40
	v_writelane_b32 v239, exec_lo, 41
	v_writelane_b32 v239, exec_hi, 42
	s_mov_b64 exec, -1
	s_lshr_b32 s75, s8, 1
	s_movk_i32 s33, 0x80
	s_lshl_b32 s9, s28, 6
	s_lshl_b32 s4, s75, 3
	s_add_i32 s16, s4, s28
	s_lshl_b32 s18, s33, 3
	s_add_u32 s6, s14, 0x40000
	s_addc_u32 s7, s15, 0
	s_add_u32 s36, s14, 0x400000
	s_addc_u32 s37, s15, 0
	s_add_u32 s34, s14, 0xb400000
	s_addc_u32 s35, s15, 0
	s_load_dwordx2 s[96:97], s[0:1], 0x98
	s_add_u32 s10, s14, 0x10c00000
	s_addc_u32 s11, s15, 0
	s_add_u32 s26, s14, 0x2a800000
	s_addc_u32 s27, s15, 0
	s_waitcnt lgkmcnt(0)
	s_cmp_lt_i32 s96, 1
	s_cselect_b64 s[4:5], -1, 0
	s_cmp_gt_i32 s97, 0
	s_cselect_b64 s[20:21], -1, 0
	s_and_b64 s[4:5], s[4:5], s[20:21]
	s_and_b64 vcc, exec, s[4:5]
	s_mul_i32 s74, s28, 0x4100
	s_cbranch_vccz .Lhce_end
	s_abs_i32 s4, s18
	v_cvt_f32_u32_e32 v0, s4
	s_sub_i32 s5, 0, s4
	s_add_i32 s19, s74, 0
	v_mbcnt_lo_u32_b32 v140, -1, 0
	v_mbcnt_hi_u32_b32 v140, -1, v140
	v_rcp_iflag_f32_e32 v0, v0
	s_nop 0
	v_mul_f32_e32 v0, 0x4f7ffffe, v0
	v_cvt_u32_f32_e32 v0, v0
	s_nop 0
	v_readfirstlane_b32 s17, v0
	s_mul_i32 s5, s5, s17
	s_mul_hi_u32 s5, s17, s5
	s_add_i32 s17, s17, s5
	s_mul_hi_u32 s5, s17, 0x9c4e
	s_mul_i32 s5, s5, s4
	s_sub_i32 s5, 0x9c4e, s5
	s_sub_i32 s17, s5, s4
	s_cmp_ge_u32 s5, s4
	s_cselect_b32 s5, s17, s5
	s_sub_i32 s17, s5, s4
	s_cmp_ge_u32 s5, s4
	s_cselect_b32 s23, s17, s5
	s_sub_i32 s22, 0x9c4e, s23
	s_add_i32 s16, s16, 0x1800
	s_mov_b32 s22, 0x3000
	s_add_u32 s0, s0, 88
	s_addc_u32 s1, s1, 0
	s_add_u32 s36, s14, 0x1a000000
	s_addc_u32 s37, s15, 0
	s_cmp_ge_i32 s16, s22
	s_cbranch_scc1 .Lhce_end
	s_cmpk_gt_i32 s16, 0x55ff
	s_cbranch_scc0 .Lhce_14
	s_cmpk_gt_u32 s16, 0x80ff
	s_cbranch_scc0 .Lhce_15
	s_add_u32 s42, s0, 48
	s_addc_u32 s43, s1, 0
	s_add_i32 s17, s16, 0x7f00
	s_and_b32 s20, s17, 0xffff
	s_mul_i32 s20, s20, 0x91a3
	s_load_dwordx2 s[4:5], s[0:1], 0x28
	s_lshr_b32 s20, s20, 23
	s_lshl_b32 s30, s20, 6
	s_mulk_i32 s20, 0xe1
	s_sub_i32 s17, s17, s20
	s_lshl_b32 s17, s17, 6
	s_and_b32 s17, s17, 0xffc0
	s_cbranch_execz .Lhce_16
	s_movk_i32 s25, 0x1040
	s_movk_i32 s24, 0x3820
	s_mov_b64 s[40:41], s[10:11]
	s_branch .Lhce_17

; #define GRID_BAR() xcd_barrier(bar)
; #define GRID_BAR() do { } while (0)
; #define BOTH(k) (IN(k) && IN((k) + 1))
; __global__ void __launch_bounds__(NWAVES * 64, 2) fwd(Args args) {
;     ...
;           for (int unit = vcu; unit < 2048; unit += G, ++it) { const int nxt = unit + G < 2048 ? unit + G : unit;
;               dn_chunk_local(unit, nxt, it & 1, sh0, sh1, xr, gpre, bpre, PROJ, args.in[7], GLOG, BETA, DNB, L, tid, lane, wave); } }
;         if (BOTH(4)) GRID_BAR();
;     }
.Lhce_end:
	s_waitcnt vmcnt(0) lgkmcnt(0)
	v_readlane_b32 s2, v239, 40
	s_mov_b32 m0, s2
	v_readlane_b32 s2, v239, 41
	v_readlane_b32 s3, v239, 42
	s_mov_b64 exec, s[2:3]
	v_readlane_b32 s0, v238, 0
	v_readlane_b32 s1, v238, 1
	v_readlane_b32 s2, v238, 2
	v_readlane_b32 s3, v238, 3
	v_readlane_b32 s4, v238, 4
	v_readlane_b32 s5, v238, 5
	v_readlane_b32 s6, v238, 6
	v_readlane_b32 s7, v238, 7
	v_readlane_b32 s8, v238, 8
	v_readlane_b32 s9, v238, 9
	v_readlane_b32 s10, v238, 10
	v_readlane_b32 s11, v238, 11
	v_readlane_b32 s12, v238, 12
	v_readlane_b32 s13, v238, 13
	v_readlane_b32 s14, v238, 14
	v_readlane_b32 s15, v238, 15
	v_readlane_b32 s16, v238, 16
	v_readlane_b32 s17, v238, 17
	v_readlane_b32 s18, v238, 18
	v_readlane_b32 s19, v238, 19
	v_readlane_b32 s20, v238, 20
	v_readlane_b32 s21, v238, 21
	v_readlane_b32 s22, v238, 22
	v_readlane_b32 s23, v238, 23
	v_readlane_b32 s24, v238, 24
	v_readlane_b32 s25, v238, 25
	v_readlane_b32 s26, v238, 26
	v_readlane_b32 s27, v238, 27
	v_readlane_b32 s28, v238, 28
	v_readlane_b32 s29, v238, 29
	v_readlane_b32 s30, v238, 30
	v_readlane_b32 s31, v238, 31
	v_readlane_b32 s32, v238, 32
	v_readlane_b32 s33, v238, 33
	v_readlane_b32 s34, v238, 34
	v_readlane_b32 s35, v238, 35
	v_readlane_b32 s36, v238, 36
	v_readlane_b32 s37, v238, 37
	v_readlane_b32 s38, v238, 38
	v_readlane_b32 s39, v238, 39
	v_readlane_b32 s40, v238, 40
	v_readlane_b32 s41, v238, 41
	v_readlane_b32 s42, v238, 42
	v_readlane_b32 s43, v238, 43
	v_readlane_b32 s44, v238, 44
	v_readlane_b32 s45, v238, 45
	v_readlane_b32 s46, v238, 46
	v_readlane_b32 s47, v238, 47
	v_readlane_b32 s48, v238, 48
	v_readlane_b32 s49, v238, 49
	v_readlane_b32 s50, v238, 50
	v_readlane_b32 s51, v238, 51
	v_readlane_b32 s52, v238, 52
	v_readlane_b32 s53, v238, 53
	v_readlane_b32 s54, v238, 54
	v_readlane_b32 s55, v238, 55
	v_readlane_b32 s56, v238, 56
	v_readlane_b32 s57, v238, 57
	v_readlane_b32 s58, v238, 58
	v_readlane_b32 s59, v238, 59
	v_readlane_b32 s60, v238, 60
	v_readlane_b32 s61, v238, 61
	v_readlane_b32 s62, v238, 62
	v_readlane_b32 s63, v238, 63
	v_readlane_b32 s64, v239, 0
	v_readlane_b32 s65, v239, 1
	v_readlane_b32 s66, v239, 2
	v_readlane_b32 s67, v239, 3
	v_readlane_b32 s68, v239, 4
	v_readlane_b32 s69, v239, 5
	v_readlane_b32 s70, v239, 6
	v_readlane_b32 s71, v239, 7
	v_readlane_b32 s72, v239, 8
	v_readlane_b32 s73, v239, 9
	v_readlane_b32 s74, v239, 10
	v_readlane_b32 s75, v239, 11
	v_readlane_b32 s76, v239, 12
	v_readlane_b32 s77, v239, 13
	v_readlane_b32 s78, v239, 14
	v_readlane_b32 s79, v239, 15
	v_readlane_b32 s80, v239, 16
	v_readlane_b32 s81, v239, 17
	v_readlane_b32 s82, v239, 18
	v_readlane_b32 s83, v239, 19
	v_readlane_b32 s84, v239, 20
	v_readlane_b32 s85, v239, 21
	v_readlane_b32 s86, v239, 22
	v_readlane_b32 s87, v239, 23
	v_readlane_b32 s88, v239, 24
	v_readlane_b32 s89, v239, 25
	v_readlane_b32 s90, v239, 26
	v_readlane_b32 s91, v239, 27
	v_readlane_b32 s92, v239, 28
	v_readlane_b32 s93, v239, 29
	v_readlane_b32 s94, v239, 30
	v_readlane_b32 s95, v239, 31
	v_readlane_b32 s96, v239, 32
	v_readlane_b32 s97, v239, 33
	v_readlane_b32 s98, v239, 34
	v_readlane_b32 s99, v239, 35
	v_readlane_b32 s100, v239, 36
	v_readlane_b32 s101, v239, 37
	v_readlane_b32 vcc_lo, v239, 38
	v_readlane_b32 vcc_hi, v239, 39

; __global__ void __launch_bounds__(NWAVES * 64, 2) fwd(Args args) {
;     ...
;           for (;;) {
;             __syncthreads();
;             if (tid == 0) MISC[16] = qpre;
;             __syncthreads();
;             constexpr int NB64 = (NCB * 3) / 4, NB16 = (NCB - NB64) * 4;
;             const unsigned q = MISC[16]; if (q >= 512u + (DEFER_AT == 5 ? (unsigned)(NB64 + NB16) : 0u)) break;
.LBB0_643:
	s_or_b64 exec, exec, s[2:3]
	s_waitcnt lgkmcnt(0)
	s_barrier
	ds_read_b32 v0, v164
	s_movk_i32 s2, 0x496
	s_waitcnt lgkmcnt(0)
	v_cmp_lt_u32_e64 s[2:3], s2, v0
	v_readfirstlane_b32 s25, v0
	s_and_b64 vcc, exec, s[2:3]
	s_cbranch_vccnz .LBB0_640
	s_and_saveexec_b64 s[6:7], s[4:5]
	s_cbranch_execz .LBB0_646
	v_mov_b32_e32 v0, v161
	s_nop 0
	v_ashrrev_i32_e32 v1, 31, v0
	v_lshl_add_u64 v[0:1], v[0:1], 2, s[44:45]
	global_atomic_add v162, v[0:1], v165, off sc0

; __global__ void __launch_bounds__(NWAVES * 64, 2) fwd(Args args) {
;     ...
;             if (!conv) attn_wg(PROJ, CONCAT, idx, L, tid, lane, wave);
;             else {
;                 const bool small = idx >= NB64; const int first = NI0 + (small ? NB64 * 64 + (idx - NB64) * 16 : idx * 64) + wave;
;                 f32x4 va[16], vb[16]; P0T_DECL(a); P0T_DECL(b);
.LBB0_679:
	s_and_b64 vcc, exec, s[4:5]
	s_cbranch_vccz .LBB0_640
	s_add_i32 s4, s25, 0xfffffe00
	s_lshl_b32 s58, s4, 4
	s_addk_i32 s58, 0xf90
	s_lshl_b32 s42, s4, 6
	s_cmpk_lt_u32 s42, 0x1000
	s_cselect_b32 s5, 0, 0x3000
	s_add_i32 s42, s42, s5
	s_cmpk_lt_u32 s58, 0x1000
	s_cselect_b32 s5, 0, 0x3000
	s_add_i32 s58, s58, s5
	s_cmpk_gt_u32 s4, 0x52
	s_cselect_b32 s5, s58, s42
	s_add_i32 s25, s86, s5
	s_cmpk_lt_u32 s4, 0x53
	s_mov_b64 s[4:5], -1
	s_cbranch_scc0 .LBB0_882
	s_add_i32 s42, s42, s28
	s_cmpk_gt_u32 s42, 0xfff
	s_cbranch_scc0 .LBB0_685
	s_cmpk_gt_u32 s42, 0x65ff
	s_cbranch_scc0 .LBB0_942
	s_and_b32 s4, s42, 0x7ffffc0
	s_add_i32 s64, s4, 0xffff9a00
	s_mov_b64 s[70:71], 0
	s_cbranch_execz .LBB0_943
